# attention: second-half load-skip test branches on SCC directly (one SALU fewer per two tiles), on top of v18
# baseline (speedup 1.0000x reference)
; #define SBAR() __builtin_amdgcn_sched_barrier(0)
; #define SLOAD(i, k0) do { sr_[i].vs0 = St::ld8(&Vh[(long)((k0) + sr) * LDK + sc]); sr_[i].vs1 = St::ld8(&Vh[(long)((k0) + 32 + sr) * LDK + sc]); \
;     sr_[i].ks0 = St::ld8(&Kh[(long)((k0) + sr) * LDK + sc]); sr_[i].ks1 = St::ld8(&Kh[(long)((k0) + 32 + sr) * LDK + sc]); } while (0)
; __device__ __forceinline__ void partialSM(f32x16& p0, f32x16& p1, float& m_reg, float& mn, float& alpha) {
;     ...
;   float mnC = -mn * C;
;   for (int r = 0; r < 16; ++r) p0[r] = fmaf(p0[r], C, mnC); for (int r = 0; r < 16; ++r) p1[r] = fmaf(p1[r], C, mnC);
;   for (int r = 0; r < 16; ++r) p0[r] = __builtin_amdgcn_exp2f(p0[r]);
; }
; __device__ __forceinline__ void finishSM(f32x16& p0, f32x16& p1, float alpha, float& l_reg, bf16x8& pa0, bf16x8& pa1, bf16x8& pa2, bf16x8& pa3) {
;   for (int r = 0; r < 16; ++r) p1[r] = __builtin_amdgcn_exp2f(p1[r]);
;   float ps = 0; for (int r = 0; r < 16; ++r) ps += p0[r]; for (int r = 0; r < 16; ++r) ps += p1[r];
;   { auto rr = __builtin_amdgcn_permlane32_swap(__float_as_uint(ps), __float_as_uint(ps), false, false);
;     ps = __uint_as_float(rr[0]) + __uint_as_float(rr[1]); }
;   l_reg = l_reg * alpha + ps;
;     ...
;   PK4(p0, 0, pa0); PK4(p0, 8, pa1); PK4(p1, 0, pa2); PK4(p1, 8, pa3);
;     ...
; }
; __device__ __forceinline__ void qkt(f32x16& p0, f32x16& p1, const bf16* Ks, const bf16x8* qr, int r32, int hi) {
;   p0 = f32x16{}; p1 = f32x16{};
;   for (int d0 = 0; d0 < 8; ++d0) { int cb = (d0 * 16 + hi * 8) * 2;
;     bf16x8 b0 = *reinterpret_cast<const bf16x8*>((const char*)Ks + KSWZ(r32, cb));
;     bf16x8 b1 = *reinterpret_cast<const bf16x8*>((const char*)Ks + KSWZ(32 + r32, cb));
;     p0 = __builtin_amdgcn_mfma_f32_32x32x16_bf16(b0, qr[d0], p0, 0, 0, 0);
;     p1 = __builtin_amdgcn_mfma_f32_32x32x16_bf16(b1, qr[d0], p1, 0, 0, 0); }
; template <typename TQ>
; __device__ __forceinline__ void attn_dense_body(const TQ* __restrict__ Qb, const bf16* __restrict__ Kh, const bf16* __restrict__ Vh,
;                                                 unsigned short* __restrict__ Ob, int seq, char* lds, const int wave_s) {
;     ...
;     if (SDEPTH == 1 || j + 3 < NT) SLOAD(SE, (j + 1 + SDEPTH) * KVBLK); SBAR();
.LBB0_579:
	v_xor_b32_e32 v189, 0x18000, v189
	v_xor_b32_e32 v199, 0x18000, v199
	v_xor_b32_e32 v192, 0x18000, v192
	v_xor_b32_e32 v191, 0x18000, v191
	v_mul_f32_e32 v207, 0xbe0293ee, v206
	v_fmamk_f32 v80, v80, 0x3e0293ee, v207
	v_fmamk_f32 v81, v81, 0x3e0293ee, v207
	v_fmamk_f32 v82, v82, 0x3e0293ee, v207
	v_fmamk_f32 v83, v83, 0x3e0293ee, v207
	v_fmamk_f32 v84, v84, 0x3e0293ee, v207
	v_fmamk_f32 v85, v85, 0x3e0293ee, v207
	v_fmamk_f32 v86, v86, 0x3e0293ee, v207
	v_fmamk_f32 v87, v87, 0x3e0293ee, v207
	v_fmamk_f32 v88, v88, 0x3e0293ee, v207
	v_fmamk_f32 v89, v89, 0x3e0293ee, v207
	v_fmamk_f32 v90, v90, 0x3e0293ee, v207
	v_fmamk_f32 v91, v91, 0x3e0293ee, v207
	v_fmamk_f32 v92, v92, 0x3e0293ee, v207
	v_fmamk_f32 v93, v93, 0x3e0293ee, v207
	v_fmamk_f32 v94, v94, 0x3e0293ee, v207
	v_fmamk_f32 v95, v95, 0x3e0293ee, v207
	v_exp_f32_e32 v160, v80
	v_exp_f32_e32 v175, v81
	v_exp_f32_e32 v161, v82
	v_exp_f32_e32 v174, v83
	v_exp_f32_e32 v162, v84
	v_exp_f32_e32 v173, v85
	v_exp_f32_e32 v163, v86
	v_exp_f32_e32 v172, v87
	v_exp_f32_e32 v164, v88
	v_exp_f32_e32 v171, v89
	v_exp_f32_e32 v165, v90
	v_exp_f32_e32 v170, v91
	v_exp_f32_e32 v166, v92
	v_exp_f32_e32 v169, v93
	v_exp_f32_e32 v167, v94
	v_exp_f32_e32 v168, v95
	v_fmamk_f32 v216, v64, 0x3e0293ee, v207
	v_fmamk_f32 v217, v65, 0x3e0293ee, v207
	v_fmamk_f32 v218, v66, 0x3e0293ee, v207
	v_fmamk_f32 v219, v67, 0x3e0293ee, v207
	v_fmamk_f32 v224, v68, 0x3e0293ee, v207
	v_fmamk_f32 v209, v69, 0x3e0293ee, v207
	v_fmamk_f32 v210, v70, 0x3e0293ee, v207
	v_fmamk_f32 v211, v71, 0x3e0293ee, v207
	v_fmamk_f32 v212, v72, 0x3e0293ee, v207
	v_fmamk_f32 v213, v73, 0x3e0293ee, v207
	v_fmamk_f32 v214, v74, 0x3e0293ee, v207
	v_fmamk_f32 v215, v75, 0x3e0293ee, v207
	v_fmamk_f32 v208, v76, 0x3e0293ee, v207
	v_fmamk_f32 v225, v77, 0x3e0293ee, v207
	v_fmamk_f32 v226, v78, 0x3e0293ee, v207
	v_fmac_f32_e32 v207, 0x3e0293ee, v79
	s_waitcnt lgkmcnt(0)
	s_barrier
	ds_read_b128 v[64:67], v189 offset:32768
	ds_read_b128 v[68:71], v189 offset:40960
	ds_read_b128 v[228:231], v199 offset:32768
	ds_read_b128 v[232:235], v199 offset:40960
	ds_read_b128 v[240:243], v192 offset:32768
	ds_read_b128 v[244:247], v192 offset:40960
	v_exp_f32_e32 v221, v207
	s_waitcnt lgkmcnt(5)
	v_mfma_f32_32x32x16_bf16 v[80:95], v[64:67], v[112:115], 0
	v_add_f32_e32 v207, v175, v160
	v_add_f32_e32 v207, v161, v207
	v_add_f32_e32 v207, v174, v207
	v_add_f32_e32 v207, v162, v207
	v_add_f32_e32 v207, v173, v207
	v_add_f32_e32 v207, v163, v207
	v_add_f32_e32 v207, v172, v207
	s_waitcnt lgkmcnt(4)
	v_mfma_f32_32x32x16_bf16 v[64:79], v[68:71], v[112:115], 0
	v_add_f32_e32 v207, v164, v207
	v_add_f32_e32 v207, v171, v207
	v_add_f32_e32 v207, v165, v207
	v_add_f32_e32 v207, v170, v207
	v_exp_f32_e32 v194, v216
	v_add_f32_e32 v207, v166, v207
	v_exp_f32_e32 v195, v217
	s_waitcnt lgkmcnt(3)
	v_mfma_f32_32x32x16_bf16 v[80:95], v[228:231], v[108:111], v[80:95]
	v_add_f32_e32 v207, v169, v207
	v_exp_f32_e32 v196, v218
	v_add_f32_e32 v207, v167, v207
	v_exp_f32_e32 v197, v219
	v_add_f32_e32 v207, v168, v207
	v_exp_f32_e32 v216, v224
	v_add_f32_e32 v207, v194, v207
	s_waitcnt lgkmcnt(2)
	v_mfma_f32_32x32x16_bf16 v[64:79], v[232:235], v[108:111], v[64:79]
	ds_read_b128 v[228:231], v191 offset:32768
	ds_read_b128 v[232:235], v191 offset:40960
	v_exp_f32_e32 v209, v209
	v_add_f32_e32 v207, v195, v207
	v_exp_f32_e32 v210, v210
	v_add_f32_e32 v207, v196, v207
	v_exp_f32_e32 v211, v211
	v_add_f32_e32 v207, v197, v207
	s_waitcnt lgkmcnt(3)
	v_mfma_f32_32x32x16_bf16 v[80:95], v[240:243], v[120:123], v[80:95]
	v_exp_f32_e32 v212, v212
	v_add_f32_e32 v207, v216, v207
	v_exp_f32_e32 v213, v213
	v_add_f32_e32 v207, v209, v207
	v_exp_f32_e32 v214, v214
	v_add_f32_e32 v207, v210, v207
	v_exp_f32_e32 v215, v215
	s_waitcnt lgkmcnt(2)
	v_mfma_f32_32x32x16_bf16 v[64:79], v[244:247], v[120:123], v[64:79]
	ds_read_b128 v[240:243], v189 offset:32896
	ds_read_b128 v[244:247], v189 offset:41088
	v_add_f32_e32 v207, v211, v207
	v_exp_f32_e32 v217, v208
	v_add_f32_e32 v207, v212, v207
	v_exp_f32_e32 v218, v225
	v_add_f32_e32 v207, v213, v207
	v_exp_f32_e32 v219, v226
	s_waitcnt lgkmcnt(3)
	v_mfma_f32_32x32x16_bf16 v[80:95], v[228:231], v[124:127], v[80:95]
	v_add_f32_e32 v207, v214, v207
	v_add_f32_e32 v207, v215, v207
	v_add_f32_e32 v207, v217, v207
	v_add_f32_e32 v207, v218, v207
	v_add_f32_e32 v207, v219, v207
	v_add_f32_e32 v207, v221, v207
	s_waitcnt lgkmcnt(2)
	v_mfma_f32_32x32x16_bf16 v[64:79], v[232:235], v[124:127], v[64:79]
	ds_read_b128 v[228:231], v199 offset:32896
	ds_read_b128 v[232:235], v199 offset:41088
	s_waitcnt lgkmcnt(3)
	v_mfma_f32_32x32x16_bf16 v[80:95], v[240:243], v[116:119], v[80:95]
	s_waitcnt lgkmcnt(2)
	v_mfma_f32_32x32x16_bf16 v[64:79], v[244:247], v[116:119], v[64:79]
	ds_read_b128 v[240:243], v192 offset:32896
	ds_read_b128 v[244:247], v192 offset:41088
	s_waitcnt lgkmcnt(3)
	v_mfma_f32_32x32x16_bf16 v[80:95], v[228:231], v[104:107], v[80:95]
	s_waitcnt lgkmcnt(2)
	v_mfma_f32_32x32x16_bf16 v[64:79], v[232:235], v[104:107], v[64:79]
	ds_read_b128 v[228:231], v191 offset:32896
	ds_read_b128 v[232:235], v191 offset:41088
	s_waitcnt lgkmcnt(3)
	v_mfma_f32_32x32x16_bf16 v[80:95], v[240:243], v[100:103], v[80:95]
	s_waitcnt lgkmcnt(2)
	v_mfma_f32_32x32x16_bf16 v[64:79], v[244:247], v[100:103], v[64:79]
	v_cvt_pk_bf16_f32 v160, v160, v175
	v_cvt_pk_bf16_f32 v161, v161, v174
	v_cvt_pk_bf16_f32 v162, v162, v173
	v_cvt_pk_bf16_f32 v163, v163, v172
	v_cvt_pk_bf16_f32 v164, v164, v171
	v_cvt_pk_bf16_f32 v165, v165, v170
	s_waitcnt lgkmcnt(1)
	v_mfma_f32_32x32x16_bf16 v[80:95], v[228:231], v[96:99], v[80:95]
	v_cvt_pk_bf16_f32 v166, v166, v169
	v_cvt_pk_bf16_f32 v167, v167, v168
	v_cvt_pk_bf16_f32 v168, v194, v195
	v_cvt_pk_bf16_f32 v169, v196, v197
	v_cvt_pk_bf16_f32 v170, v216, v209
	v_cvt_pk_bf16_f32 v171, v210, v211
	v_cvt_pk_bf16_f32 v172, v212, v213
	s_waitcnt lgkmcnt(0)
	v_mfma_f32_32x32x16_bf16 v[64:79], v[232:235], v[96:99], v[64:79]
	v_cvt_pk_bf16_f32 v173, v214, v215
	v_cvt_pk_bf16_f32 v174, v217, v218
	v_cvt_pk_bf16_f32 v175, v219, v221
	s_add_i32 s50, s50, 2
	s_cmp_ge_u32 s50, s49
	s_cselect_b64 s[44:45], -1, 0
	s_cbranch_scc1 .Lattn_skip_loads
	global_load_dwordx4 v[128:131], v176, s[52:53]
	global_load_dwordx4 v[132:135], v176, s[52:53] offset:-512
	s_add_u32 s52, s52, 0x18000
	s_addc_u32 s53, s53, 0
	global_load_dwordx4 v[136:139], v176, s[52:53]
	global_load_dwordx4 v[140:143], v176, s[52:53] offset:-512
	s_add_u32 s52, s52, 0x18000
	s_addc_u32 s53, s53, 0
